# rms_rows loops inside the w_out phases: 4 row loads issued together and next row prefetched, instead of load-wait one at a time
# speedup vs baseline: 1.0084x; 1.0084x over previous
;     static __device__ __forceinline__ float gv(unsigned long long gw, int i) { return __uint_as_float((unsigned)((gw >> (16 * i)) & 0xffffull) << 16); }
; __device__ __forceinline__ float opq(float v) { asm volatile("" : "+v"(v)); return v; }
; __device__ __forceinline__ unsigned pk2(float lo, float hi) { f32x2_t v = {lo, hi}; bf16x2_t b = __builtin_convertvector(v, bf16x2_t); return __builtin_bit_cast(unsigned, b); }
; __device__ __forceinline__ void rms_rows(const float* x, const float* gain, bf16_t* out, int nrows, int gw, int NGW, int lane) {
;     f32x4 gv[4];
; #pragma unroll
;     for (int j = 0; j < 4; ++j) gv[j] = *((const f32x4*)gain + lane + 64 * j);
;     for (int m = gw; m < nrows; m += NGW) {
;         const f32x4* xr = (const f32x4*)(x + (size_t)m * DM) + lane; f32x4 v[4]; float ss = 0.f;
; #pragma unroll
;         for (int j = 0; j < 4; ++j) { v[j] = xr[64 * j]; ss += (v[j].x * v[j].x + v[j].y * v[j].y) + (v[j].z * v[j].z + v[j].w * v[j].w); }
;         const float rstd = rsqrtf(wave_sum(ss, lane) * (1.f / DM) + opq(EPS));
;         u32x2* o = (u32x2*)(out + (size_t)m * DM) + lane;
; #pragma unroll
;         for (int j = 0; j < 4; ++j) { u32x2 w; w.x = pk2(v[j].x * rstd * gv[j].x, v[j].y * rstd * gv[j].y); w.y = pk2(v[j].z * rstd * gv[j].z, v[j].w * rstd * gv[j].w); o[64 * j] = w; }
;     }
.LBB0_359:
	s_andn2_b64 vcc, exec, s[2:3]
	s_cbranch_vccnz .LBB0_385
	s_mul_i32 s0, s30, s82
	s_add_i32 s2, s0, s79
	v_readlane_b32 s0, v254, 32
	s_lshl_b32 s4, s0, 10
	s_ashr_i32 s5, s4, 31
	v_ashrrev_i32_e32 v131, 31, v130
	s_mov_b64 s[6:7], -1
	s_and_b64 vcc, exec, s[58:59]
	v_readlane_b32 s1, v254, 33
	s_cbranch_vccz .LBB0_381
	v_readlane_b32 s8, v254, 30
	s_cmpk_gt_i32 s2, 0x1fff
	v_readlane_b32 s9, v254, 31
	s_cbranch_scc1 .LBB0_364
	v_readlane_b32 s10, v254, 36
	v_readlane_b32 s11, v254, 37
	s_load_dwordx2 s[0:1], s[10:11], 0xc0
	s_lshl_b64 s[6:7], s[4:5], 2
	v_lshlrev_b64 v[20:21], 4, v[130:131]
	v_lshlrev_b32_e32 v18, 2, v130
	v_xor_b32_e32 v0, 4, v18
	s_waitcnt lgkmcnt(0)
	s_add_u32 s0, s0, s6
	s_addc_u32 s1, s1, s7
	v_lshl_add_u64 v[14:15], s[0:1], 0, v[20:21]
	global_load_dwordx4 v[2:5], v[14:15], off offset:3072
	global_load_dwordx4 v[6:9], v[14:15], off offset:2048
	global_load_dwordx4 v[10:13], v[14:15], off offset:1024
	s_nop 0
	global_load_dwordx4 v[14:17], v[14:15], off
	s_load_dwordx2 s[0:1], s[10:11], 0xd8
	s_ashr_i32 s3, s2, 31
	s_lshl_b64 s[6:7], s[2:3], 11
	s_add_u32 s6, s94, s6
	s_addc_u32 s7, s95, s7
	v_xor_b32_e32 v22, 8, v18
	v_xor_b32_e32 v23, 16, v18
	v_xor_b32_e32 v24, 32, v18
	v_xor_b32_e32 v25, 64, v18
	v_lshl_add_u64 v[18:19], v[130:131], 3, s[6:7]
	s_lshl_b64 s[6:7], s[2:3], 12
	s_waitcnt lgkmcnt(0)
	s_add_u32 s0, s0, s6
	s_addc_u32 s1, s1, s7
	v_lshl_add_u64 v[20:21], s[0:1], 0, v[20:21]
	v_readlane_b32 s0, v254, 19
	s_mov_b64 s[6:7], 0xc00
	v_readlane_b32 s1, v254, 20
	v_lshl_add_u64 v[20:21], v[20:21], 0, s[6:7]
	s_mov_b32 s3, s2
	global_load_dwordx4 v[46:49], v[20:21], off offset:-3072
	global_load_dwordx4 v[50:53], v[20:21], off offset:-2048
	global_load_dwordx4 v[54:57], v[20:21], off offset:-1024
	global_load_dwordx4 v[58:61], v[20:21], off
	s_waitcnt vmcnt(0)
	s_branch .Lrms363_body
.LBB0_363:
	s_waitcnt vmcnt(4)
.Lrms363_body:
	v_mov_b32_e32 v26, v46
	v_mov_b32_e32 v27, v47
	v_mov_b32_e32 v28, v48
	v_mov_b32_e32 v29, v49
	v_mov_b32_e32 v30, v50
	v_mov_b32_e32 v31, v51
	v_mov_b32_e32 v32, v52
	v_mov_b32_e32 v33, v53
	v_mov_b32_e32 v34, v54
	v_mov_b32_e32 v35, v55
	v_mov_b32_e32 v36, v56
	v_mov_b32_e32 v37, v57
	v_mov_b32_e32 v38, v58
	v_mov_b32_e32 v39, v59
	v_mov_b32_e32 v40, v60
	v_mov_b32_e32 v41, v61
	s_add_i32 s3, s3, s78
	s_cmpk_lt_i32 s3, 0x2000
	s_cbranch_scc0 .Lrms363_nopf
	v_lshl_add_u64 v[20:21], v[20:21], 0, s[0:1]
	global_load_dwordx4 v[46:49], v[20:21], off offset:-3072
	global_load_dwordx4 v[50:53], v[20:21], off offset:-2048
	global_load_dwordx4 v[54:57], v[20:21], off offset:-1024
	global_load_dwordx4 v[58:61], v[20:21], off
.Lrms363_nopf:
	v_mul_f32_e32 v62, v27, v27
	v_mul_f32_e32 v63, v29, v29
	v_fmac_f32_e32 v62, v26, v26
	v_fmac_f32_e32 v63, v28, v28
	v_add_f32_e32 v42, v62, v63
	v_mul_f32_e32 v62, v31, v31
	v_mul_f32_e32 v63, v33, v33
	v_fmac_f32_e32 v62, v30, v30
	v_fmac_f32_e32 v63, v32, v32
	v_add_f32_e32 v62, v62, v63
	v_add_f32_e32 v42, v42, v62
	v_mul_f32_e32 v62, v35, v35
	v_mul_f32_e32 v63, v37, v37
	v_fmac_f32_e32 v62, v34, v34
	v_fmac_f32_e32 v63, v36, v36
	v_add_f32_e32 v62, v62, v63
	v_add_f32_e32 v42, v42, v62
	v_mul_f32_e32 v62, v39, v39
	v_mul_f32_e32 v63, v41, v41
	v_fmac_f32_e32 v62, v38, v38
	v_fmac_f32_e32 v63, v40, v40
	v_add_f32_e32 v62, v62, v63
	v_add_f32_e32 v42, v42, v62
	ds_bpermute_b32 v43, v0, v42
	s_waitcnt lgkmcnt(0)
	v_add_f32_e32 v42, v42, v43
	ds_bpermute_b32 v43, v22, v42
	s_waitcnt lgkmcnt(0)
	v_add_f32_e32 v42, v42, v43
	ds_bpermute_b32 v43, v23, v42
	s_waitcnt lgkmcnt(0)
	v_add_f32_e32 v42, v42, v43
	ds_bpermute_b32 v43, v24, v42
	s_waitcnt lgkmcnt(0)
	v_add_f32_e32 v42, v42, v43
	ds_bpermute_b32 v43, v25, v42
	s_waitcnt lgkmcnt(0)
	v_add_f32_e32 v42, v42, v43
	v_mov_b32_e32 v43, v42
	s_nop 1
	v_permlane32_swap_b32_e32 v42, v43
	v_add_f32_e32 v42, v42, v43
	v_mov_b32_e32 v43, 0x358637bd
	s_nop 0
	v_fmac_f32_e32 v43, 0x3a800000, v42
	v_cmp_gt_f32_e32 vcc, s57, v43
	v_mul_f32_e32 v42, 0x4b800000, v43
	s_nop 0
	v_cndmask_b32_e32 v42, v43, v42, vcc
	v_rsq_f32_e32 v42, v42
	s_nop 0
	v_mul_f32_e32 v43, 0x45800000, v42
	v_cndmask_b32_e32 v42, v42, v43, vcc
	v_pk_mul_f32 v[26:27], v[26:27], v[42:43] op_sel_hi:[1,0]
	v_pk_mul_f32 v[28:29], v[28:29], v[42:43] op_sel_hi:[1,0]
	v_pk_mul_f32 v[26:27], v[14:15], v[26:27]
	v_pk_mul_f32 v[28:29], v[16:17], v[28:29]
	v_cvt_pk_bf16_f32 v26, v26, v27
	v_cvt_pk_bf16_f32 v27, v28, v29
	global_store_dwordx2 v[18:19], v[26:27], off
	v_pk_mul_f32 v[26:27], v[30:31], v[42:43] op_sel_hi:[1,0]
	v_pk_mul_f32 v[28:29], v[32:33], v[42:43] op_sel_hi:[1,0]
	v_pk_mul_f32 v[26:27], v[10:11], v[26:27]
	v_pk_mul_f32 v[28:29], v[12:13], v[28:29]
	v_cvt_pk_bf16_f32 v26, v26, v27
	v_cvt_pk_bf16_f32 v27, v28, v29
	global_store_dwordx2 v[18:19], v[26:27], off offset:512
	v_pk_mul_f32 v[26:27], v[34:35], v[42:43] op_sel_hi:[1,0]
	v_pk_mul_f32 v[28:29], v[36:37], v[42:43] op_sel_hi:[1,0]
	v_pk_mul_f32 v[26:27], v[6:7], v[26:27]
	v_pk_mul_f32 v[28:29], v[8:9], v[28:29]
	v_cvt_pk_bf16_f32 v26, v26, v27
	v_cvt_pk_bf16_f32 v27, v28, v29
	global_store_dwordx2 v[18:19], v[26:27], off offset:1024
	v_pk_mul_f32 v[26:27], v[38:39], v[42:43] op_sel_hi:[1,0]
	v_pk_mul_f32 v[28:29], v[40:41], v[42:43] op_sel_hi:[1,0]
	v_pk_mul_f32 v[26:27], v[2:3], v[26:27]
	v_pk_mul_f32 v[28:29], v[4:5], v[28:29]
	v_cvt_pk_bf16_f32 v26, v26, v27
	v_cvt_pk_bf16_f32 v27, v28, v29
	global_store_dwordx2 v[18:19], v[26:27], off offset:1536
	v_lshl_add_u64 v[18:19], v[18:19], 0, s[8:9]
	s_cmpk_lt_i32 s3, 0x2000
	s_cbranch_scc1 .LBB0_363

;     static __device__ __forceinline__ float gv(unsigned long long gw, int i) { return __uint_as_float((unsigned)((gw >> (16 * i)) & 0xffffull) << 16); }
; __device__ __forceinline__ void rms_rows(const float* x, const float* gain, bf16_t* out, int nrows, int gw, int NGW, int lane) {
;     f32x4 gv[4];
; #pragma unroll
;     for (int j = 0; j < 4; ++j) gv[j] = *((const f32x4*)gain + lane + 64 * j);
;     for (int m = gw; m < nrows; m += NGW) {
;         const f32x4* xr = (const f32x4*)(x + (size_t)m * DM) + lane; f32x4 v[4]; float ss = 0.f;
; __global__ void __launch_bounds__(512, 2) mega_fwd(Args A_) {
;     ...
;             if (sub == 7 && rep == 0) {
;                 const int widx = gwb, nw = NGW;
;                 if (grp == 0) rms_rows(A.out() + (size_t)TG * DM, A.in(I_MIXN) + L * DM, hbuf, TG, widx, nw, lane);
;                 else { rms_rows(A.out(), A.in(I_F2N) + L * DM, hbuf, TG, widx, nw, lane);
.LBB0_381:
	s_and_b64 vcc, exec, s[6:7]
	s_cbranch_vccz .LBB0_385
	s_cmpk_gt_i32 s2, 0x1fff
	s_cbranch_scc1 .LBB0_385
	v_readlane_b32 s6, v254, 36
	v_readlane_b32 s7, v254, 37
	s_load_dwordx2 s[0:1], s[6:7], 0x20
	s_lshl_b64 s[4:5], s[4:5], 2
	v_lshlrev_b64 v[18:19], 4, v[130:131]
	v_lshlrev_b32_e32 v20, 2, v130
	v_xor_b32_e32 v0, 4, v20
	s_waitcnt lgkmcnt(0)
	s_add_u32 s0, s0, s4
	s_addc_u32 s1, s1, s5
	v_lshl_add_u64 v[14:15], s[0:1], 0, v[18:19]
	global_load_dwordx4 v[2:5], v[14:15], off offset:3072
	global_load_dwordx4 v[6:9], v[14:15], off offset:2048
	global_load_dwordx4 v[10:13], v[14:15], off offset:1024
	s_nop 0
	global_load_dwordx4 v[14:17], v[14:15], off
	s_load_dwordx2 s[0:1], s[6:7], 0xd8
	s_ashr_i32 s3, s2, 31
	s_lshl_b64 s[4:5], s[2:3], 12
	v_xor_b32_e32 v22, 8, v20
	v_xor_b32_e32 v23, 16, v20
	s_waitcnt lgkmcnt(0)
	s_add_u32 s0, s0, s4
	s_addc_u32 s1, s1, s5
	v_lshl_add_u64 v[18:19], s[0:1], 0, v[18:19]
	s_mov_b64 s[0:1], 0x2000000
	v_lshl_add_u64 v[18:19], v[18:19], 0, s[0:1]
	s_lshl_b64 s[0:1], s[2:3], 11
	s_add_u32 s0, s94, s0
	s_addc_u32 s1, s95, s1
	v_xor_b32_e32 v24, 32, v20
	v_xor_b32_e32 v25, 64, v20
	v_lshl_add_u64 v[20:21], v[130:131], 3, s[0:1]
	global_load_dwordx4 v[46:49], v[18:19], off
	global_load_dwordx4 v[50:53], v[18:19], off offset:1024
	global_load_dwordx4 v[54:57], v[18:19], off offset:2048
	global_load_dwordx4 v[58:61], v[18:19], off offset:3072
	s_waitcnt vmcnt(0)
	s_branch .Lrms384_body

;     static __device__ __forceinline__ float gv(unsigned long long gw, int i) { return __uint_as_float((unsigned)((gw >> (16 * i)) & 0xffffull) << 16); }
; __device__ __forceinline__ float opq(float v) { asm volatile("" : "+v"(v)); return v; }
; __device__ __forceinline__ unsigned pk2(float lo, float hi) { f32x2_t v = {lo, hi}; bf16x2_t b = __builtin_convertvector(v, bf16x2_t); return __builtin_bit_cast(unsigned, b); }
; __device__ __forceinline__ void rms_rows(const float* x, const float* gain, bf16_t* out, int nrows, int gw, int NGW, int lane) {
;     ...
;     for (int m = gw; m < nrows; m += NGW) {
;         const f32x4* xr = (const f32x4*)(x + (size_t)m * DM) + lane; f32x4 v[4]; float ss = 0.f;
; #pragma unroll
;         for (int j = 0; j < 4; ++j) { v[j] = xr[64 * j]; ss += (v[j].x * v[j].x + v[j].y * v[j].y) + (v[j].z * v[j].z + v[j].w * v[j].w); }
;         const float rstd = rsqrtf(wave_sum(ss, lane) * (1.f / DM) + opq(EPS));
;         u32x2* o = (u32x2*)(out + (size_t)m * DM) + lane;
; #pragma unroll
;         for (int j = 0; j < 4; ++j) { u32x2 w; w.x = pk2(v[j].x * rstd * gv[j].x, v[j].y * rstd * gv[j].y); w.y = pk2(v[j].z * rstd * gv[j].z, v[j].w * rstd * gv[j].w); o[64 * j] = w; }
;     }
.Lrms384_body:
	v_mov_b32_e32 v26, v46
	v_mov_b32_e32 v27, v47
	v_mov_b32_e32 v28, v48
	v_mov_b32_e32 v29, v49
	v_mov_b32_e32 v30, v50
	v_mov_b32_e32 v31, v51
	v_mov_b32_e32 v32, v52
	v_mov_b32_e32 v33, v53
	v_mov_b32_e32 v34, v54
	v_mov_b32_e32 v35, v55
	v_mov_b32_e32 v36, v56
	v_mov_b32_e32 v37, v57
	v_mov_b32_e32 v38, v58
	v_mov_b32_e32 v39, v59
	v_mov_b32_e32 v40, v60
	v_mov_b32_e32 v41, v61
	v_readlane_b32 s0, v254, 19
	v_readlane_b32 s1, v254, 20
	s_add_i32 s2, s2, s78
	s_cmpk_gt_i32 s2, 0x1fff
	s_cbranch_scc1 .Lrms384_nopf
	v_lshl_add_u64 v[18:19], v[18:19], 0, s[0:1]
	global_load_dwordx4 v[46:49], v[18:19], off
	global_load_dwordx4 v[50:53], v[18:19], off offset:1024
	global_load_dwordx4 v[54:57], v[18:19], off offset:2048
	global_load_dwordx4 v[58:61], v[18:19], off offset:3072
.Lrms384_nopf:
	v_readlane_b32 s0, v254, 30
	v_readlane_b32 s1, v254, 31
	v_mul_f32_e32 v62, v27, v27
	v_mul_f32_e32 v63, v29, v29
	v_fmac_f32_e32 v62, v26, v26
	v_fmac_f32_e32 v63, v28, v28
	v_add_f32_e32 v42, v62, v63
	v_mul_f32_e32 v62, v31, v31
	v_mul_f32_e32 v63, v33, v33
	v_fmac_f32_e32 v62, v30, v30
	v_fmac_f32_e32 v63, v32, v32
	v_add_f32_e32 v62, v62, v63
	v_add_f32_e32 v42, v42, v62
	v_mul_f32_e32 v62, v35, v35
	v_mul_f32_e32 v63, v37, v37
	v_fmac_f32_e32 v62, v34, v34
	v_fmac_f32_e32 v63, v36, v36
	v_add_f32_e32 v62, v62, v63
	v_add_f32_e32 v42, v42, v62
	v_mul_f32_e32 v62, v39, v39
	v_mul_f32_e32 v63, v41, v41
	v_fmac_f32_e32 v62, v38, v38
	v_fmac_f32_e32 v63, v40, v40
	v_add_f32_e32 v62, v62, v63
	v_add_f32_e32 v42, v42, v62
	ds_bpermute_b32 v43, v0, v42
	s_waitcnt lgkmcnt(0)
	v_add_f32_e32 v42, v42, v43
	ds_bpermute_b32 v43, v22, v42
	s_waitcnt lgkmcnt(0)
	v_add_f32_e32 v42, v42, v43
	ds_bpermute_b32 v43, v23, v42
	s_waitcnt lgkmcnt(0)
	v_add_f32_e32 v42, v42, v43
	ds_bpermute_b32 v43, v24, v42
	s_waitcnt lgkmcnt(0)
	v_add_f32_e32 v42, v42, v43
	ds_bpermute_b32 v43, v25, v42
	s_waitcnt lgkmcnt(0)
	v_add_f32_e32 v42, v42, v43
	v_mov_b32_e32 v43, v42
	s_nop 1
	v_permlane32_swap_b32_e32 v42, v43
	v_add_f32_e32 v42, v42, v43
	v_mov_b32_e32 v43, 0x358637bd
	s_nop 0
	v_fmac_f32_e32 v43, 0x3a800000, v42
	v_cmp_gt_f32_e32 vcc, s57, v43
	v_mul_f32_e32 v42, 0x4b800000, v43
	s_nop 0
	v_cndmask_b32_e32 v42, v43, v42, vcc
	v_rsq_f32_e32 v42, v42
	s_nop 0
	v_mul_f32_e32 v43, 0x45800000, v42
	v_cndmask_b32_e32 v42, v42, v43, vcc
	v_pk_mul_f32 v[26:27], v[26:27], v[42:43] op_sel_hi:[1,0]
	v_pk_mul_f32 v[28:29], v[28:29], v[42:43] op_sel_hi:[1,0]
	v_pk_mul_f32 v[26:27], v[14:15], v[26:27]
	v_pk_mul_f32 v[28:29], v[16:17], v[28:29]
	v_cvt_pk_bf16_f32 v26, v26, v27
	v_cvt_pk_bf16_f32 v27, v28, v29
	global_store_dwordx2 v[20:21], v[26:27], off
	v_pk_mul_f32 v[26:27], v[30:31], v[42:43] op_sel_hi:[1,0]
	v_pk_mul_f32 v[28:29], v[32:33], v[42:43] op_sel_hi:[1,0]
	v_pk_mul_f32 v[26:27], v[10:11], v[26:27]
	v_pk_mul_f32 v[28:29], v[12:13], v[28:29]
	v_cvt_pk_bf16_f32 v26, v26, v27
	v_cvt_pk_bf16_f32 v27, v28, v29
	global_store_dwordx2 v[20:21], v[26:27], off offset:512
	v_pk_mul_f32 v[26:27], v[34:35], v[42:43] op_sel_hi:[1,0]
	v_pk_mul_f32 v[28:29], v[36:37], v[42:43] op_sel_hi:[1,0]
	v_pk_mul_f32 v[26:27], v[6:7], v[26:27]
	v_pk_mul_f32 v[28:29], v[8:9], v[28:29]
	v_cvt_pk_bf16_f32 v26, v26, v27
	v_cvt_pk_bf16_f32 v27, v28, v29
	global_store_dwordx2 v[20:21], v[26:27], off offset:1024
	v_pk_mul_f32 v[26:27], v[38:39], v[42:43] op_sel_hi:[1,0]
	v_pk_mul_f32 v[28:29], v[40:41], v[42:43] op_sel_hi:[1,0]
	v_pk_mul_f32 v[26:27], v[2:3], v[26:27]
	v_pk_mul_f32 v[28:29], v[4:5], v[28:29]
	v_cvt_pk_bf16_f32 v26, v26, v27
	v_cvt_pk_bf16_f32 v27, v28, v29
	global_store_dwordx2 v[20:21], v[26:27], off offset:1536
	v_lshl_add_u64 v[20:21], v[20:21], 0, s[0:1]
	s_cmpk_gt_i32 s2, 0x1fff
	s_cbranch_scc0 .LBB0_384
